# on top of v25: HGRN2 output phase fragment reads (state, QH, V^T, K^T, A tiles) issued as conflict-free ds_read_b64 pairs (K halves swapped consistently for odd k-chunk lanes in both MFMA operands) in
# speedup vs baseline: 1.0011x; 1.0011x over previous
; #define LAS __attribute__((address_space(3)))
; __device__ __forceinline__ void hgrn_r3(const GAS bf16* proj, const GAS float* RU, const GAS float* RD, GAS bf16* y, int TOKG, const GAS float* ogain, unsigned char* lds, int tid, int lane, int wave, int bid, int G) {
;     ...
;     const int nruns = (TOKG / SEQ) * 16 * (128 / RUNC);
;     const int fr = lane & 15, fq = lane >> 4;
;     unsigned rq[8], rg[8], rv[8];
;     unsigned voff[8], zoff[4], yoff[4];
; #pragma unroll
;     for (int i = 0; i < 8; ++i) voff[i] = (unsigned)((wave * 8 + i) * (PW * 2) + lane * 4);
; #pragma unroll
;     for (int t2 = 0; t2 < 4; ++t2) { zoff[t2] = (unsigned)(((16 * t2 + fr) * PW + 16 * wave + 4 * fq) * 2); yoff[t2] = (unsigned)(((16 * t2 + fr) * MW + 16 * wave + 4 * fq) * 2); }
;     const __amdgpu_buffer_rsrc_t prs = __builtin_amdgcn_make_buffer_rsrc((void*)proj, 0, (int)((size_t)TOKG * PW * 2), 0x00020000);
;     ...
;     for (int run = bid; run < nruns; run += G) {
;         const int u0 = run * RUNC, seq = run / (128 / RUNC), rr = run - seq * (128 / RUNC), h = seq & 15, bl = seq >> 4;
; __device__ __forceinline__ Ctx load_ctx(LAS unsigned long long* ptab) {
;     Ctx c; const int step = (int)ldptr(ptab, 16); c.NG = (int)ldptr(ptab, 15); c.layer = step / c.NG; c.g = step - c.layer * c.NG; c.TOKG = NTOK / c.NG; c.j = c.layer >> 1; c.even = !(c.layer & 1);
.LBB0_374:
	s_abs_i32 s5, s4
	v_cvt_f32_u32_e32 v0, s5
	s_sub_i32 s8, 0, s5
	s_ashr_i32 s7, s3, 31
	s_abs_i32 s3, s3
	v_rcp_iflag_f32_e32 v0, v0
	s_ashr_i32 s4, s4, 31
	s_xor_b32 s7, s7, s4
	v_and_b32_e32 v99, 63, v98
	v_mul_f32_e32 v0, 0x4f7ffffe, v0
	v_cvt_u32_f32_e32 v0, v0
	s_nop 0
	v_readfirstlane_b32 s9, v0
	s_mul_i32 s8, s8, s9
	s_mul_hi_u32 s8, s9, s8
	s_add_i32 s9, s9, s8
	s_mul_hi_u32 s8, s3, s9
	s_mul_i32 s10, s8, s5
	s_sub_i32 s3, s3, s10
	s_add_i32 s11, s8, 1
	s_sub_i32 s10, s3, s5
	s_cmp_ge_u32 s3, s5
	s_cselect_b32 s8, s11, s8
	s_cselect_b32 s3, s10, s3
	s_add_i32 s10, s8, 1
	s_cmp_ge_u32 s3, s5
	s_cselect_b32 s3, s10, s8
	s_lshr_b32 s8, s9, 17
	s_xor_b32 s3, s3, s7
	s_mul_i32 s9, s8, s5
	s_sub_i32 s7, s3, s7
	s_sub_i32 s3, 0x8000, s9
	s_add_i32 s9, s8, 1
	s_sub_i32 s10, s3, s5
	s_cmp_ge_u32 s3, s5
	s_cselect_b32 s8, s9, s8
	s_cselect_b32 s3, s10, s3
	s_add_i32 s9, s8, 1
	s_cmp_ge_u32 s3, s5
	s_cselect_b32 s3, s9, s8
	s_xor_b32 s3, s3, s4
	s_sub_i32 s96, s3, s4
	s_ashr_i32 s97, s96, 31
	s_ashr_i32 s3, s7, 1
	s_ashr_i32 s40, s6, 6
	s_lshl_b64 s[98:99], s[96:97], 14
	s_bitcmp1_b32 s7, 0
	s_cselect_b64 s[8:9], -1, 0
	s_mov_b64 s[4:5], -1
	s_and_b64 vcc, exec, s[8:9]
	s_cbranch_vccz .LBB0_401
	v_readlane_b32 s4, v236, 30
	s_nop 1
	v_mov_b32_e32 v0, s4
	ds_read_b64 v[0:1], v0
	s_ashr_i32 s4, s96, 31
	s_lshr_b32 s4, s4, 19
	s_add_i32 s5, s96, s4
	s_ashr_i32 s5, s5, 13
	s_lshl_b32 s53, s5, 7
	s_waitcnt lgkmcnt(0)
	v_readfirstlane_b32 s4, v1
	s_cmp_ge_i32 s2, s53
	v_readfirstlane_b32 s5, v0
	s_cbranch_scc1 .LBB0_400
	s_add_u32 s44, s0, 0x1800000
	s_addc_u32 s56, s1, 0
	s_lshl_b32 s46, s96, 14
	s_and_b32 s45, s56, 0xffff
	s_add_u32 s57, s44, s98
	s_addc_u32 s74, s56, s99
	s_lshl_b64 s[8:9], s[96:97], 12
	s_add_u32 s8, s57, s8
	s_addc_u32 s9, s74, s9
	s_lshl_b32 s10, s3, 11
	s_ashr_i32 s11, s10, 31
	s_lshl_b64 s[10:11], s[10:11], 2
	v_lshrrev_b32_e32 v2, 4, v99
	s_add_u32 s10, s5, s10
	v_lshlrev_b32_e32 v0, 2, v99
	v_lshlrev_b32_e32 v3, 2, v2
	s_addc_u32 s11, s4, s11
	s_lshl_b32 s75, s40, 4
	v_lshl_or_b32 v100, s40, 17, v0
	v_and_b32_e32 v4, 15, v98
	v_or_b32_e32 v0, s75, v3
	v_or_b32_e32 v1, 48, v4
	v_lshlrev_b32_e32 v5, 1, v0
	v_lshl_add_u32 v68, v1, 12, v5
	s_movk_i32 s4, 0x3000
	v_mad_u32_u24 v70, v1, s4, v68
	v_or_b32_e32 v1, 32, v4
	v_lshl_add_u32 v72, v1, 12, v5
	v_mad_u32_u24 v74, v1, s4, v72
	v_or_b32_e32 v1, 16, v4
	v_lshl_add_u32 v76, v1, 12, v5
	v_mad_u32_u24 v78, v1, s4, v76
	s_waitcnt vmcnt(0)
	v_lshl_add_u32 v80, v4, 12, v5
	v_ashrrev_i32_e32 v1, 31, v0
	v_or_b32_e32 v5, s75, v4
	v_lshl_add_u64 v[84:85], v[0:1], 2, s[10:11]
	v_lshlrev_b32_e32 v0, 7, v5
	v_mad_u32_u24 v82, v4, s4, v80
	s_lshl_b32 s4, s40, 2
	v_ashrrev_i32_e32 v1, 31, v0
	s_add_i32 s4, s4, 0
	v_lshl_add_u64 v[0:1], v[0:1], 2, s[8:9]
	v_and_b32_e32 v112, 48, v99
	s_add_i32 s42, s4, 0x14800
	v_lshl_add_u64 v[86:87], v[0:1], 0, v[112:113]
	v_lshl_add_u64 v[0:1], s[0:1], 0, v[112:113]
	s_mov_b64 s[4:5], 0x1410000
	s_movk_i32 s25, 0x110
	v_lshl_add_u64 v[88:89], v[0:1], 0, s[4:5]
	v_mul_lo_u32 v0, v5, s25
	v_readlane_b32 s4, v236, 31
	s_add_i32 s5, 0, 0x13800
	v_lshlrev_b32_e32 v1, 3, v99
	v_add_u32_e32 v108, s4, v0
	s_lshl_b32 s4, s40, 9
	s_add_i32 s4, s5, s4
	v_add_u32_e32 v116, s5, v1
	v_readlane_b32 s5, v236, 32
	s_movk_i32 s7, 0x120
	s_add_i32 s43, s5, s75
	v_add_u32_e32 v110, s4, v1
	v_mad_u32_u24 v111, v99, s7, 0
	s_movk_i32 s4, 0xfee4
	s_cmp_lt_u32 s6, 64
	v_mad_i32_i24 v6, v99, s4, v111
	s_cselect_b64 s[70:71], -1, 0
	s_ashr_i32 s22, s6, 7
	s_lshl_b32 s4, s40, 1
	v_mov_b32_e32 v7, s5
	s_and_b32 s23, s4, 2
	v_lshl_or_b32 v8, s22, 4, v4
	s_movk_i32 s4, 0x90
	v_and_b32_e32 v109, 48, v98
	v_mad_u32_u24 v7, v99, s7, v7
	v_mul_lo_u32 v9, v8, s4
	v_readlane_b32 s6, v236, 33
	v_readlane_b32 s7, v236, 34
	s_cmp_gt_i32 s40, 0
	v_add_u32_e32 v9, s6, v9
	v_add_u32_e32 v117, s7, v112
	v_add_u32_e32 v13, s6, v109
	v_add_u32_e32 v120, s7, v1
	s_cselect_b64 s[6:7], -1, 0
	s_cmp_gt_i32 s40, 1
	s_cselect_b64 s[8:9], -1, 0
	s_cmp_gt_i32 s40, 2
	s_cselect_b64 s[10:11], -1, 0
	s_cmp_gt_i32 s40, 3
	s_cselect_b64 s[12:13], -1, 0
	s_cmp_gt_i32 s40, 4
	s_cselect_b64 s[14:15], -1, 0
	s_cmp_gt_i32 s40, 5
	s_cselect_b64 s[16:17], -1, 0
	s_cmp_gt_i32 s40, 6
	v_and_b32_e32 v15, 64, v190
	s_cselect_b64 s[18:19], -1, 0
	s_cmp_gt_i32 s40, 7
	v_xor_b32_e32 v14, 16, v190
	v_add_u32_e32 v15, 64, v15
	s_cselect_b64 s[20:21], -1, 0
	s_cmp_le_i32 s23, s22
	v_cmp_lt_i32_e32 vcc, v14, v15
	s_cselect_b64 s[82:83], -1, 0
	s_lshl_b32 s24, s23, 4
	v_cndmask_b32_e32 v14, v190, v14, vcc
	s_cmp_lt_i32 s23, s22
	v_or_b32_e32 v18, s24, v3
	v_lshlrev_b32_e32 v118, 2, v14
	v_xor_b32_e32 v14, 32, v190
	s_cselect_b64 s[48:49], -1, 0
	s_or_b32 s30, s24, 16
	v_or_b32_e32 v19, 2, v18
	v_cmp_lt_i32_e32 vcc, v14, v15
	v_cmp_gt_i32_e64 s[26:27], v19, v8
	v_or_b32_e32 v19, 3, v18
	v_or_b32_e32 v3, s30, v3
	v_lshlrev_b32_e32 v0, 3, v2
	v_mul_lo_u32 v10, v8, s25
	v_mul_lo_u32 v5, v5, s4
	v_cndmask_b32_e32 v14, v190, v14, vcc
	v_lshlrev_b32_e32 v15, 5, v4
	v_or_b32_e32 v1, s24, v4
	v_or_b32_e32 v16, s30, v4
	v_cmp_gt_i32_e64 s[28:29], v19, v8
	v_or_b32_e32 v19, 2, v3
	v_mul_u32_u24_e32 v2, 0x120, v99
	v_add_u32_e32 v10, 0, v10
	v_add_u32_e32 v11, 0, v109
	v_add_u32_e32 v5, 0, v5
	v_add_u32_e32 v12, s5, v109
	v_lshlrev_b32_e32 v119, 2, v14
	v_lshlrev_b32_e32 v14, 5, v99
	s_mul_i32 s54, s40, 0x880
	v_mad_u32_u24 v1, v1, s25, 0
	v_mad_u32_u24 v16, v16, s25, 0
	v_mul_u32_u24_e32 v17, 0x110, v4
	v_mul_u32_u24_e32 v4, 0x90, v4
	v_cmp_gt_i32_e64 s[22:23], v18, v8
	v_cmp_lt_i32_e64 s[24:25], v18, v8
	v_lshlrev_b32_e32 v18, 1, v18
	v_cmp_gt_i32_e64 s[30:31], v3, v8
	v_cmp_lt_i32_e64 s[34:35], v3, v8
	v_cmp_gt_i32_e64 s[36:37], v19, v8
	v_or_b32_e32 v19, 3, v3
	v_lshlrev_b32_e32 v3, 1, v3
	v_add_u32_e32 v121, v108, v0
	v_add_u32_e32 v0, 0, v15
	v_or_b32_e32 v101, 0x4000, v100
	v_or_b32_e32 v102, 0x8000, v100
	v_or_b32_e32 v103, 0xc000, v100
	v_or_b32_e32 v104, 0x10000, v100
	v_or_b32_e32 v105, 0x14000, v100
	v_or_b32_e32 v106, 0x18000, v100
	v_or_b32_e32 v107, 0x1c000, v100
	v_cmp_gt_u32_e64 s[4:5], 16, v99
	v_mov_b32_e32 v83, v113
	v_mov_b32_e32 v79, v113
	v_mov_b32_e32 v75, v113
	v_mov_b32_e32 v71, v113
	v_mov_b32_e32 v81, v113
	v_mov_b32_e32 v77, v113
	v_mov_b32_e32 v73, v113
	v_mov_b32_e32 v69, v113
	v_cmp_gt_i32_e64 s[38:39], v19, v8
	v_add_u32_e32 v122, s54, v6
	v_add_u32_e32 v123, s75, v7
	v_add_u32_e32 v124, s43, v2
	v_add_u32_e32 v125, v1, v109
	v_add_u32_e32 v126, v9, v18
	v_add_u32_e32 v127, v16, v109
	v_add_u32_e32 v128, v9, v3
	v_add_u32_e32 v129, v11, v17
	v_add_u32_e32 v130, v5, v109
	v_add_u32_e32 v131, v12, v4
	v_add_u32_e32 v132, v13, v4
	v_and_b32_e32 v213, 16, v190
	v_lshrrev_b32_e32 v213, 1, v213
	v_add_u32_e32 v129, v129, v213
	v_add_u32_e32 v130, v130, v213
	v_add_u32_e32 v131, v131, v213
	v_add_u32_e32 v132, v132, v213
	v_add_u32_e32 v133, 0x14800, v0
	v_add_u32_e32 v134, v10, v109
	v_add_u32_e32 v135, s42, v14
	v_readlane_b32 s76, v236, 18
	v_readlane_b32 s68, v236, 17
	v_readlane_b32 s87, v236, 16
	v_readlane_b32 s94, v236, 15
	s_mov_b32 s97, s2
	s_branch .LBB0_378

; #define LAS __attribute__((address_space(3)))
; #define GAS __attribute__((address_space(1)))
; __device__ __forceinline__ unsigned pkbf(float lo, float hi) { const f32x2_t v = {lo, hi}; const bf16x2_t b = __builtin_convertvector(v, bf16x2_t); return __builtin_bit_cast(unsigned, b); }
; __device__ __forceinline__ float lo16(unsigned w) { return __uint_as_float(w << 16); }
; __device__ __forceinline__ float hi16(unsigned w) { return __uint_as_float(w & 0xffff0000u); }
; __device__ __forceinline__ void hgrn_r3(const GAS bf16* proj, const GAS float* RU, const GAS float* RD, GAS bf16* y, int TOKG, const GAS float* ogain, unsigned char* lds, int tid, int lane, int wave, int bid, int G) {
;     ...
;             const int u = u0 + ci, cch = u & 127;
;             const size_t rowc = (size_t)bl * SEQ + cch * 64;
;             v2u zw[4];
;             { const GAS char* zb = (const GAS char*)(proj + rowc * PW + 6144 + h * 128);
; #pragma unroll
;               for (int t2 = 0; t2 < 4; ++t2) zw[t2] = *(const GAS v2u*)(zb + zoff[t2]); }
;             bf16x8 sf[4];
;             { LAS unsigned char* sl = L + H3_SL + (16 * wave + fr) * HQS;
; #pragma unroll
;               for (int nk = 0; nk < 8; ++nk) { v2u w; w.x = pkbf(Sm[nk][0], Sm[nk][1]); w.y = pkbf(Sm[nk][2], Sm[nk][3]); *(LAS v2u*)(sl + (16 * nk + 4 * fq) * 2) = w; }
; #pragma unroll
;               for (int ks = 0; ks < 4; ++ks) sf[ks] = *(const LAS bf16x8*)(sl + (32 * ks + 8 * fq) * 2); }
;             float f0[8], f1[8], qv0[8], qv1[8]; float run0 = 0.f, run1 = 0.f; v4u vv0, vv1;
;             { float p0 = 1.f, p1 = 1.f;
; #pragma unroll
;               for (int i = 0; i < 8; ++i) { const float g0 = lo16(rg[i]), g1 = hi16(rg[i]); run0 += g0; run1 += g1; f0[i] = __builtin_amdgcn_exp2f(g0); f1[i] = __builtin_amdgcn_exp2f(g1);
;                   p0 *= f0[i]; p1 *= f1[i]; qv0[i] = lo16(rq[i]) * p0; qv1[i] = hi16(rq[i]) * p1; } }
;             vv0.x = (rv[0] & 0xffffu) | (rv[1] << 16); vv0.y = (rv[2] & 0xffffu) | (rv[3] << 16); vv0.z = (rv[4] & 0xffffu) | (rv[5] << 16); vv0.w = (rv[6] & 0xffffu) | (rv[7] << 16);
;             vv1.x = (rv[0] >> 16) | (rv[1] & 0xffff0000u); vv1.y = (rv[2] >> 16) | (rv[3] & 0xffff0000u); vv1.z = (rv[4] >> 16) | (rv[5] & 0xffff0000u); vv1.w = (rv[6] >> 16) | (rv[7] & 0xffff0000u);
;             if (ci + 1 < RUNC) H3_LOAD(u + 1);
.LBB0_384:
	s_and_b32 s42, s81, 0x1fc0
	s_or_b32 s42, s54, s42
	s_mov_b32 s43, s55
	s_lshl_b64 vcc, s[42:43], 14
	s_add_u32 s64, s44, vcc_lo
	s_addc_u32 s65, s56, vcc_hi
	s_add_u32 s64, s64, s60
	s_addc_u32 s65, s65, 0
	s_add_u32 vcc_lo, s64, 0x3000
	s_addc_u32 vcc_hi, s65, 0
	v_lshl_add_u64 v[36:37], vcc, 0, v[82:83]
	v_lshl_add_u64 v[38:39], vcc, 0, v[78:79]
	v_lshl_add_u64 v[40:41], vcc, 0, v[74:75]
	v_lshl_add_u64 v[42:43], vcc, 0, v[70:71]
	global_load_dwordx2 v[96:97], v[36:37], off
	global_load_dwordx2 v[94:95], v[38:39], off
	global_load_dwordx2 v[92:93], v[40:41], off
	global_load_dwordx2 v[90:91], v[42:43], off
	v_cvt_pk_bf16_f32 v36, v20, v21
	v_cvt_pk_bf16_f32 v37, v22, v23
	v_cvt_pk_bf16_f32 v38, v4, v5
	v_cvt_pk_bf16_f32 v39, v6, v7
	ds_write2_b64 v121, v[36:37], v[38:39] offset1:4
	v_cvt_pk_bf16_f32 v36, v16, v17
	v_cvt_pk_bf16_f32 v37, v18, v19
	v_cvt_pk_bf16_f32 v38, v8, v9
	v_cvt_pk_bf16_f32 v39, v10, v11
	ds_write2_b64 v121, v[36:37], v[38:39] offset0:8 offset1:12
	v_cvt_pk_bf16_f32 v36, v24, v25
	v_cvt_pk_bf16_f32 v37, v26, v27
	v_cvt_pk_bf16_f32 v38, v12, v13
	v_cvt_pk_bf16_f32 v39, v14, v15
	ds_write2_b64 v121, v[36:37], v[38:39] offset0:16 offset1:20
	v_cvt_pk_bf16_f32 v36, v28, v29
	v_cvt_pk_bf16_f32 v37, v30, v31
	v_cvt_pk_bf16_f32 v38, v32, v33
	v_cvt_pk_bf16_f32 v39, v34, v35
	ds_write2_b64 v121, v[36:37], v[38:39] offset0:24 offset1:28
	v_add_u32_e32 v234, v108, v109
	v_add_u32_e32 v234, v234, v213
	v_xor_b32_e32 v235, 8, v234
	ds_read_b64 v[48:49], v234
	ds_read_b64 v[50:51], v235
	ds_read_b64 v[44:45], v234 offset:64
	ds_read_b64 v[46:47], v235 offset:64
	ds_read_b64 v[40:41], v234 offset:128
	ds_read_b64 v[42:43], v235 offset:128
	ds_read_b64 v[36:37], v234 offset:192
	ds_read_b64 v[38:39], v235 offset:192
	s_cmp_eq_u32 s80, 15
	s_cbranch_scc1 .LBB0_386
	s_add_i32 s64, s94, s80
	s_and_b32 s65, s77, 0x3f80000
	s_and_b32 s64, s64, 0x780
	s_and_b32 vcc_lo, s69, 0x7c000000
	s_or_b32 s64, s65, s64
	s_or_b32 s64, s64, vcc_lo
	s_lshl_b32 s64, s64, 1
	s_or_b32 s65, s64, 0x1000
	s_or_b32 vcc_lo, s64, 0x2000
	buffer_load_dword v139, v100, s[44:47], s64 offen
	buffer_load_dword v115, v100, s[44:47], s65 offen
	buffer_load_dword v112, v100, s[44:47], vcc_lo offen
	buffer_load_dword v142, v101, s[44:47], s64 offen
	buffer_load_dword v137, v101, s[44:47], s65 offen
	buffer_load_dword v114, v101, s[44:47], vcc_lo offen
	buffer_load_dword v145, v102, s[44:47], s64 offen
	buffer_load_dword v140, v102, s[44:47], s65 offen
	buffer_load_dword v136, v102, s[44:47], vcc_lo offen
	buffer_load_dword v148, v103, s[44:47], s64 offen
	buffer_load_dword v143, v103, s[44:47], s65 offen
	buffer_load_dword v138, v103, s[44:47], vcc_lo offen
	buffer_load_dword v151, v104, s[44:47], s64 offen
	buffer_load_dword v146, v104, s[44:47], s65 offen
	buffer_load_dword v141, v104, s[44:47], vcc_lo offen
	buffer_load_dword v153, v105, s[44:47], s64 offen
	buffer_load_dword v149, v105, s[44:47], s65 offen
	buffer_load_dword v144, v105, s[44:47], vcc_lo offen
	buffer_load_dword v155, v106, s[44:47], s64 offen
	buffer_load_dword v152, v106, s[44:47], s65 offen
	buffer_load_dword v147, v106, s[44:47], vcc_lo offen
	buffer_load_dword v156, v107, s[44:47], s64 offen
	buffer_load_dword v154, v107, s[44:47], s65 offen
	buffer_load_dword v150, v107, s[44:47], vcc_lo offen

; #define LAS __attribute__((address_space(3)))
; __device__ __forceinline__ unsigned pkbf(float lo, float hi) { const f32x2_t v = {lo, hi}; const bf16x2_t b = __builtin_convertvector(v, bf16x2_t); return __builtin_bit_cast(unsigned, b); }
; #define MFMA16(a, b, c) __builtin_amdgcn_mfma_f32_16x16x32_bf16((a), (b), (c), 0, 0, 0)
; __device__ __forceinline__ void hgrn_r3(const GAS bf16* proj, const GAS float* RU, const GAS float* RD, GAS bf16* y, int TOKG, const GAS float* ogain, unsigned char* lds, int tid, int lane, int wave, int bid, int G) {
;     ...
;                   const int t = 16 * tt + fr, s0 = 16 * ss + 4 * fq;
;                   v2u w; w.x = pkbf(s0 <= t ? a[0] : 0.f, s0 + 1 <= t ? a[1] : 0.f); w.y = pkbf(s0 + 2 <= t ? a[2] : 0.f, s0 + 3 <= t ? a[3] : 0.f);
;                   *(LAS v2u*)(L + H3_AM + t * HS + s0 * 2) = w; } }
;             f32x4h acc[4];
; #pragma unroll
;             for (int t2 = 0; t2 < 4; ++t2) acc[t2] = (f32x4h){0.f, 0.f, 0.f, 0.f};
; #pragma unroll
;             for (int t2 = 0; t2 < 4; ++t2)
; #pragma unroll
;                 for (int ks = 0; ks < 4; ++ks) { const bf16x8 qf = *(const LAS bf16x8*)(L + H3_QH + (16 * t2 + fr) * HQS + (32 * ks + 8 * fq) * 2); acc[t2] = MFMA16(sf[ks], qf, acc[t2]); }
;             bf16x8 vf[2];
; #pragma unroll
;             for (int ks = 0; ks < 2; ++ks) vf[ks] = *(const LAS bf16x8*)(L + H3_VT + (16 * wave + fr) * HS + (32 * ks + 8 * fq) * 2);
; #pragma unroll
;             for (int nk = 0; nk < 8; ++nk) { const f32x4h dk = *(const LAS f32x4h*)(decl + 16 * nk + 4 * fq); Sm[nk] = Sm[nk] * dk;
; #pragma unroll
;                 for (int ks = 0; ks < 2; ++ks) { const bf16x8 kf = *(const LAS bf16x8*)(L + H3_KT + (16 * nk + fr) * HS + (32 * ks + 8 * fq) * 2); Sm[nk] = MFMA16(kf, vf[ks], Sm[nk]); } }
;             __syncthreads();
.LBB0_392:
	s_nop 7
	v_cndmask_b32_e64 v52, v52, 0, s[30:31]
	v_cndmask_b32_e64 v53, 0, v53, s[34:35]
	v_cvt_pk_bf16_f32 v52, v52, v53
	v_cndmask_b32_e64 v53, v54, 0, s[36:37]
	v_cndmask_b32_e64 v54, v55, 0, s[38:39]
	v_cvt_pk_bf16_f32 v53, v53, v54
	ds_write_b64 v128, v[52:53]
	v_xor_b32_e32 v234, 8, v129
	ds_read_b64 v[214:215], v129
	ds_read_b64 v[216:217], v234
	ds_read_b64 v[218:219], v129 offset:64
	ds_read_b64 v[220:221], v234 offset:64
	ds_read_b64 v[222:223], v129 offset:128
	ds_read_b64 v[224:225], v234 offset:128
	ds_read_b64 v[226:227], v129 offset:192
	ds_read_b64 v[228:229], v234 offset:192
	ds_read_b64 v[230:231], v129 offset:4352
	ds_read_b64 v[232:233], v234 offset:4352
	ds_read_b64 v[64:65], v129 offset:4416
	ds_read_b64 v[66:67], v234 offset:4416
	s_waitcnt lgkmcnt(10)
	v_mfma_f32_16x16x32_bf16 v[52:55], v[48:51], v[214:217], 0
	ds_read_b64 v[214:215], v129 offset:4480
	ds_read_b64 v[216:217], v234 offset:4480
	s_waitcnt lgkmcnt(10)
	v_mfma_f32_16x16x32_bf16 v[52:55], v[44:47], v[218:221], v[52:55]
	ds_read_b64 v[218:219], v129 offset:4544
	ds_read_b64 v[220:221], v234 offset:4544
	s_waitcnt lgkmcnt(10)
	v_mfma_f32_16x16x32_bf16 v[52:55], v[40:43], v[222:225], v[52:55]
	ds_read_b64 v[222:223], v129 offset:8704
	ds_read_b64 v[224:225], v234 offset:8704
	s_waitcnt lgkmcnt(10)
	v_mfma_f32_16x16x32_bf16 v[52:55], v[36:39], v[226:229], v[52:55]
	ds_read_b64 v[226:227], v129 offset:8768
	ds_read_b64 v[228:229], v234 offset:8768
	s_waitcnt lgkmcnt(10)
	v_mfma_f32_16x16x32_bf16 v[56:59], v[48:51], v[230:233], 0
	ds_read_b64 v[230:231], v129 offset:8832
	ds_read_b64 v[232:233], v234 offset:8832
	s_waitcnt lgkmcnt(10)
	v_mfma_f32_16x16x32_bf16 v[56:59], v[44:47], v[64:67], v[56:59]
	ds_read_b64 v[64:65], v129 offset:8896
	ds_read_b64 v[66:67], v234 offset:8896
	s_waitcnt lgkmcnt(10)
	v_mfma_f32_16x16x32_bf16 v[56:59], v[40:43], v[214:217], v[56:59]
	ds_read_b64 v[214:215], v129 offset:13056
	ds_read_b64 v[216:217], v234 offset:13056
	s_waitcnt lgkmcnt(10)
	v_mfma_f32_16x16x32_bf16 v[56:59], v[36:39], v[218:221], v[56:59]
	ds_read_b64 v[218:219], v129 offset:13120
	ds_read_b64 v[220:221], v234 offset:13120
	s_waitcnt lgkmcnt(10)
	v_mfma_f32_16x16x32_bf16 v[60:63], v[48:51], v[222:225], 0
	ds_read_b64 v[222:223], v129 offset:13184
	ds_read_b64 v[224:225], v234 offset:13184
	s_waitcnt lgkmcnt(10)
	v_mfma_f32_16x16x32_bf16 v[60:63], v[44:47], v[226:229], v[60:63]
	ds_read_b64 v[226:227], v129 offset:13248
	ds_read_b64 v[228:229], v234 offset:13248
	s_waitcnt lgkmcnt(10)
	v_mfma_f32_16x16x32_bf16 v[60:63], v[40:43], v[230:233], v[60:63]
	s_waitcnt lgkmcnt(8)
	v_mfma_f32_16x16x32_bf16 v[60:63], v[36:39], v[64:67], v[60:63]
	s_waitcnt lgkmcnt(6)
	v_mfma_f32_16x16x32_bf16 v[48:51], v[48:51], v[214:217], 0
	s_waitcnt lgkmcnt(4)
	v_mfma_f32_16x16x32_bf16 v[44:47], v[44:47], v[218:221], v[48:51]
	s_waitcnt lgkmcnt(2)
	v_mfma_f32_16x16x32_bf16 v[40:43], v[40:43], v[222:225], v[44:47]
	s_waitcnt lgkmcnt(0)
	v_mfma_f32_16x16x32_bf16 v[40:43], v[36:39], v[226:229], v[40:43]
	s_nop 3
	v_xor_b32_e32 v234, 8, v130
	v_xor_b32_e32 v235, 8, v131
	ds_read_b64 v[44:45], v130 offset:52224
	ds_read_b64 v[46:47], v234 offset:52224
	ds_read_b64 v[36:37], v130 offset:52288
	ds_read_b64 v[38:39], v234 offset:52288
	ds_read_b128 v[48:51], v117
	ds_read_b64 v[214:215], v131
	ds_read_b64 v[216:217], v235
	ds_read_b64 v[218:219], v131 offset:64
	ds_read_b64 v[220:221], v235 offset:64
	ds_read_b128 v[222:225], v117 offset:64
	ds_read_b64 v[226:227], v131 offset:2304
	ds_read_b64 v[228:229], v235 offset:2304
	ds_read_b64 v[230:231], v131 offset:2368
	ds_read_b64 v[232:233], v235 offset:2368
	s_waitcnt lgkmcnt(7)
	v_pk_mul_f32 v[22:23], v[22:23], v[50:51]
	v_pk_mul_f32 v[20:21], v[20:21], v[48:49]
	s_nop 1
	v_mfma_f32_16x16x32_bf16 v[20:23], v[214:217], v[44:47], v[20:23]
	s_waitcnt lgkmcnt(5)
	v_mfma_f32_16x16x32_bf16 v[20:23], v[218:221], v[36:39], v[20:23]
	ds_read_b128 v[48:51], v117 offset:128
	ds_read_b64 v[214:215], v131 offset:4608
	ds_read_b64 v[216:217], v235 offset:4608
	ds_read_b64 v[218:219], v131 offset:4672
	ds_read_b64 v[220:221], v235 offset:4672
	s_waitcnt lgkmcnt(7)
	v_pk_mul_f32 v[6:7], v[6:7], v[224:225]
	v_pk_mul_f32 v[4:5], v[4:5], v[222:223]
	s_nop 1
	v_mfma_f32_16x16x32_bf16 v[4:7], v[226:229], v[44:47], v[4:7]
	s_waitcnt lgkmcnt(5)
	v_mfma_f32_16x16x32_bf16 v[4:7], v[230:233], v[36:39], v[4:7]
	ds_read_b128 v[222:225], v117 offset:192
	ds_read_b64 v[226:227], v131 offset:6912
	ds_read_b64 v[228:229], v235 offset:6912
	ds_read_b64 v[230:231], v131 offset:6976
	ds_read_b64 v[232:233], v235 offset:6976
	s_waitcnt lgkmcnt(7)
	v_pk_mul_f32 v[18:19], v[18:19], v[50:51]
	v_pk_mul_f32 v[16:17], v[16:17], v[48:49]
	s_nop 1
	v_mfma_f32_16x16x32_bf16 v[16:19], v[214:217], v[44:47], v[16:19]
	s_waitcnt lgkmcnt(5)
	v_mfma_f32_16x16x32_bf16 v[16:19], v[218:221], v[36:39], v[16:19]
	ds_read_b128 v[48:51], v117 offset:256
	ds_read_b64 v[214:215], v131 offset:9216
	ds_read_b64 v[216:217], v235 offset:9216
	ds_read_b64 v[218:219], v131 offset:9280
	ds_read_b64 v[220:221], v235 offset:9280
	s_waitcnt lgkmcnt(7)
	v_pk_mul_f32 v[10:11], v[10:11], v[224:225]
	v_pk_mul_f32 v[8:9], v[8:9], v[222:223]
	s_nop 1
	v_mfma_f32_16x16x32_bf16 v[8:11], v[226:229], v[44:47], v[8:11]
	s_waitcnt lgkmcnt(5)
	v_mfma_f32_16x16x32_bf16 v[8:11], v[230:233], v[36:39], v[8:11]
	ds_read_b128 v[222:225], v117 offset:320
	ds_read_b64 v[226:227], v131 offset:11520
	ds_read_b64 v[228:229], v235 offset:11520
	ds_read_b64 v[230:231], v131 offset:11584
	ds_read_b64 v[232:233], v235 offset:11584
	s_waitcnt lgkmcnt(7)
	v_pk_mul_f32 v[26:27], v[26:27], v[50:51]
	v_pk_mul_f32 v[24:25], v[24:25], v[48:49]
	s_nop 1
	v_mfma_f32_16x16x32_bf16 v[24:27], v[214:217], v[44:47], v[24:27]
	s_waitcnt lgkmcnt(5)
	v_mfma_f32_16x16x32_bf16 v[24:27], v[218:221], v[36:39], v[24:27]
	ds_read_b128 v[48:51], v117 offset:384
	ds_read_b64 v[214:215], v131 offset:13824
	ds_read_b64 v[216:217], v235 offset:13824
	ds_read_b64 v[218:219], v131 offset:13888
	ds_read_b64 v[220:221], v235 offset:13888
	s_waitcnt lgkmcnt(7)
	v_pk_mul_f32 v[14:15], v[14:15], v[224:225]
	v_pk_mul_f32 v[12:13], v[12:13], v[222:223]
	s_nop 1
	v_mfma_f32_16x16x32_bf16 v[12:15], v[226:229], v[44:47], v[12:15]
	s_waitcnt lgkmcnt(5)
	v_mfma_f32_16x16x32_bf16 v[12:15], v[230:233], v[36:39], v[12:15]
	ds_read_b128 v[222:225], v117 offset:448
	ds_read_b64 v[226:227], v131 offset:16128
	ds_read_b64 v[228:229], v235 offset:16128
	ds_read_b64 v[230:231], v131 offset:16192
	ds_read_b64 v[232:233], v235 offset:16192
	s_waitcnt lgkmcnt(7)
	v_pk_mul_f32 v[30:31], v[30:31], v[50:51]
	v_pk_mul_f32 v[28:29], v[28:29], v[48:49]
	s_nop 1
	v_mfma_f32_16x16x32_bf16 v[28:31], v[214:217], v[44:47], v[28:31]
	s_waitcnt lgkmcnt(5)
	v_mfma_f32_16x16x32_bf16 v[28:31], v[218:221], v[36:39], v[28:31]
	s_waitcnt lgkmcnt(2)
	v_pk_mul_f32 v[34:35], v[34:35], v[224:225]
	v_pk_mul_f32 v[32:33], v[32:33], v[222:223]
	s_nop 1
	v_mfma_f32_16x16x32_bf16 v[32:35], v[226:229], v[44:47], v[32:35]
	s_waitcnt lgkmcnt(0)
	s_barrier
; #define LAS __attribute__((address_space(3)))
; #define MFMA16(a, b, c) __builtin_amdgcn_mfma_f32_16x16x32_bf16((a), (b), (c), 0, 0, 0)
; __device__ __forceinline__ void hgrn_r3(const GAS bf16* proj, const GAS float* RU, const GAS float* RD, GAS bf16* y, int TOKG, const GAS float* ogain, unsigned char* lds, int tid, int lane, int wave, int bid, int G) {
;     ...
; #pragma unroll
;             for (int t2 = 0; t2 < 4; ++t2)
; #pragma unroll
;                 for (int ks = 0; ks < 2; ++ks) { const bf16x8 af = *(const LAS bf16x8*)(L + H3_AM + (16 * t2 + fr) * HS + (32 * ks + 8 * fq) * 2); acc[t2] = MFMA16(vf[ks], af, acc[t2]); }
; #pragma unroll
;             for (int t2 = 0; t2 < 4; ++t2) { float ss = acc[t2][0] * acc[t2][0] + acc[t2][1] * acc[t2][1] + acc[t2][2] * acc[t2][2] + acc[t2][3] * acc[t2][3];
;                 ss += __shfl_xor(ss, 16); ss += __shfl_xor(ss, 32); if (fq == 0) red[(16 * t2 + fr) * 8 + wave] = ss; }
	v_mfma_f32_16x16x32_bf16 v[32:35], v[230:233], v[36:39], v[32:35]
	v_xor_b32_e32 v234, 8, v132
	ds_read_b64 v[48:49], v132
	ds_read_b64 v[50:51], v234
	s_waitcnt lgkmcnt(0)
	v_mfma_f32_16x16x32_bf16 v[48:51], v[44:47], v[48:51], v[52:55]
	s_nop 2
	ds_read_b64 v[52:53], v132 offset:64
	ds_read_b64 v[54:55], v234 offset:64
	s_waitcnt lgkmcnt(0)
	v_mfma_f32_16x16x32_bf16 v[64:67], v[36:39], v[52:55], v[48:51]
	ds_read_b64 v[52:53], v132 offset:2368
	ds_read_b64 v[54:55], v234 offset:2368
	s_nop 1
	ds_read_b64 v[48:49], v132 offset:2304
	ds_read_b64 v[50:51], v234 offset:2304
	s_waitcnt lgkmcnt(0)
	v_mfma_f32_16x16x32_bf16 v[48:51], v[44:47], v[48:51], v[56:59]
	s_nop 2
	ds_read_b64 v[56:57], v132 offset:4672
	ds_read_b64 v[58:59], v234 offset:4672
	v_mfma_f32_16x16x32_bf16 v[52:55], v[36:39], v[52:55], v[48:51]
	s_nop 2
	ds_read_b64 v[48:49], v132 offset:4608
	ds_read_b64 v[50:51], v234 offset:4608
	s_waitcnt lgkmcnt(0)
	v_mfma_f32_16x16x32_bf16 v[48:51], v[44:47], v[48:51], v[60:63]
	v_mfma_f32_16x16x32_bf16 v[48:51], v[36:39], v[56:59], v[48:51]
	ds_read_b64 v[56:57], v132 offset:6912
	ds_read_b64 v[58:59], v234 offset:6912
	s_waitcnt lgkmcnt(0)
	v_mfma_f32_16x16x32_bf16 v[40:43], v[44:47], v[56:59], v[40:43]
	ds_read_b64 v[44:45], v132 offset:6976
	ds_read_b64 v[46:47], v234 offset:6976
	s_waitcnt lgkmcnt(0)
	v_mfma_f32_16x16x32_bf16 v[36:39], v[36:39], v[44:47], v[40:43]
	s_nop 4
	v_mul_f32_e32 v40, v65, v65
	v_fmac_f32_e32 v40, v64, v64
	v_fmac_f32_e32 v40, v66, v66
	v_fmac_f32_e32 v40, v67, v67
	ds_bpermute_b32 v41, v118, v40
	s_waitcnt lgkmcnt(0)
	v_add_f32_e32 v40, v40, v41
	ds_bpermute_b32 v41, v119, v40
	s_and_saveexec_b64 vcc, s[4:5]
	s_cbranch_execz .LBB0_394
	s_waitcnt lgkmcnt(0)
	v_add_f32_e32 v40, v40, v41
	ds_write_b32 v135, v40
